# full grid barrier: non-leader workgroups poll the top generation word directly (skips the per-XCD generation hop) at the 3 executed flushing seams
# speedup vs baseline: 1.0011x; 1.0011x over previous
.LBB0_432:
	v_readlane_b32 s4, v252, 26
	v_readlane_b32 s5, v252, 27
	v_cvt_f32_u32_e32 v1, v2
	v_sub_u32_e32 v4, 0, v2
	v_rcp_iflag_f32_e32 v1, v1
	s_nop 1
	global_atomic_add v3, v145, v195, s[4:5] sc0
	v_mul_f32_e32 v1, 0x4f7ffffe, v1
	v_cvt_u32_f32_e32 v1, v1
	v_mul_lo_u32 v4, v4, v1
	v_mul_hi_u32 v4, v1, v4
	v_add_u32_e32 v1, v1, v4
	s_waitcnt vmcnt(0)
	v_mul_hi_u32 v1, v3, v1
	v_mul_lo_u32 v4, v1, v2
	v_sub_u32_e32 v4, v3, v4
	v_add_u32_e32 v5, 1, v1
	v_cmp_ge_u32_e32 vcc, v4, v2
	v_add_u32_e32 v3, 1, v3
	s_nop 0
	v_cndmask_b32_e32 v1, v1, v5, vcc
	v_sub_u32_e32 v5, v4, v2
	v_cndmask_b32_e32 v4, v4, v5, vcc
	v_add_u32_e32 v5, 1, v1
	v_cmp_ge_u32_e32 vcc, v4, v2
	s_nop 1
	v_cndmask_b32_e32 v1, v1, v5, vcc
	v_mul_lo_u32 v4, v2, v1
	v_add_u32_e32 v2, v4, v2
	v_cmp_ne_u32_e32 vcc, v3, v2
	s_and_saveexec_b64 s[4:5], vcc
	s_xor_b64 s[4:5], exec, s[4:5]
	s_cbranch_execz .LBB0_446
	v_readlane_b32 s6, v252, 32
	v_readlane_b32 s7, v252, 33
	s_waitcnt lgkmcnt(0)
	s_nop 3
	global_load_dword v0, v145, s[6:7] sc1
	s_waitcnt vmcnt(0)
	v_cmp_eq_u32_e32 vcc, v0, v1
	s_and_saveexec_b64 s[6:7], vcc
	s_cbranch_execz .LBB0_445
	s_mov_b32 s8, 1
	s_mov_b64 s[18:19], 0
	s_branch .LBB0_436

.LBB0_438:
	v_readlane_b32 s10, v252, 32
	v_readlane_b32 s11, v252, 33
	s_add_i32 s8, s8, 1
	s_mov_b64 s[38:39], -1
	s_nop 2
	global_load_dword v0, v145, s[10:11] sc1
	s_waitcnt vmcnt(0)
	v_cmp_ne_u32_e32 vcc, v0, v1
	s_orn2_b64 s[36:37], vcc, exec
	s_branch .LBB0_435

.LBB0_568:
	v_readlane_b32 s4, v252, 26
	v_readlane_b32 s5, v252, 27
	v_cvt_f32_u32_e32 v1, v2
	v_sub_u32_e32 v4, 0, v2
	v_rcp_iflag_f32_e32 v1, v1
	s_nop 1
	global_atomic_add v3, v145, v195, s[4:5] sc0
	v_mul_f32_e32 v1, 0x4f7ffffe, v1
	v_cvt_u32_f32_e32 v1, v1
	v_mul_lo_u32 v4, v4, v1
	v_mul_hi_u32 v4, v1, v4
	v_add_u32_e32 v1, v1, v4
	s_waitcnt vmcnt(0)
	v_mul_hi_u32 v1, v3, v1
	v_mul_lo_u32 v4, v1, v2
	v_sub_u32_e32 v4, v3, v4
	v_add_u32_e32 v5, 1, v1
	v_cmp_ge_u32_e32 vcc, v4, v2
	v_add_u32_e32 v3, 1, v3
	s_nop 0
	v_cndmask_b32_e32 v1, v1, v5, vcc
	v_sub_u32_e32 v5, v4, v2
	v_cndmask_b32_e32 v4, v4, v5, vcc
	v_add_u32_e32 v5, 1, v1
	v_cmp_ge_u32_e32 vcc, v4, v2
	s_nop 1
	v_cndmask_b32_e32 v1, v1, v5, vcc
	v_mul_lo_u32 v4, v2, v1
	v_add_u32_e32 v2, v4, v2
	v_cmp_ne_u32_e32 vcc, v3, v2
	s_and_saveexec_b64 s[4:5], vcc
	s_xor_b64 s[4:5], exec, s[4:5]
	s_cbranch_execz .LBB0_582
	v_readlane_b32 s6, v252, 32
	v_readlane_b32 s7, v252, 33
	s_waitcnt lgkmcnt(0)
	s_nop 3
	global_load_dword v0, v145, s[6:7] sc1
	s_waitcnt vmcnt(0)
	v_cmp_eq_u32_e32 vcc, v0, v1
	s_and_saveexec_b64 s[6:7], vcc
	s_cbranch_execz .LBB0_581
	s_mov_b32 s8, 1
	s_mov_b64 s[12:13], 0
	s_branch .LBB0_572

.LBB0_574:
	v_readlane_b32 s10, v252, 32
	v_readlane_b32 s11, v252, 33
	s_add_i32 s8, s8, 1
	s_mov_b64 s[36:37], -1
	s_nop 2
	global_load_dword v0, v145, s[10:11] sc1
	s_waitcnt vmcnt(0)
	v_cmp_ne_u32_e32 vcc, v0, v1
	s_orn2_b64 s[24:25], vcc, exec
	s_branch .LBB0_571

.LBB0_1084:
	v_readlane_b32 s8, v252, 26
	v_readlane_b32 s9, v252, 27
	v_cvt_f32_u32_e32 v1, v2
	v_sub_u32_e32 v4, 0, v2
	v_rcp_iflag_f32_e32 v1, v1
	s_nop 1
	global_atomic_add v3, v145, v195, s[8:9] sc0
	v_mul_f32_e32 v1, 0x4f7ffffe, v1
	v_cvt_u32_f32_e32 v1, v1
	v_mul_lo_u32 v4, v4, v1
	v_mul_hi_u32 v4, v1, v4
	v_add_u32_e32 v1, v1, v4
	s_waitcnt vmcnt(0)
	v_mul_hi_u32 v1, v3, v1
	v_mul_lo_u32 v4, v1, v2
	v_sub_u32_e32 v4, v3, v4
	v_add_u32_e32 v5, 1, v1
	v_cmp_ge_u32_e32 vcc, v4, v2
	v_add_u32_e32 v3, 1, v3
	s_nop 0
	v_cndmask_b32_e32 v1, v1, v5, vcc
	v_sub_u32_e32 v5, v4, v2
	v_cndmask_b32_e32 v4, v4, v5, vcc
	v_add_u32_e32 v5, 1, v1
	v_cmp_ge_u32_e32 vcc, v4, v2
	s_nop 1
	v_cndmask_b32_e32 v1, v1, v5, vcc
	v_mul_lo_u32 v4, v2, v1
	v_add_u32_e32 v2, v4, v2
	v_cmp_ne_u32_e32 vcc, v3, v2
	s_and_saveexec_b64 s[8:9], vcc
	s_xor_b64 s[12:13], exec, s[8:9]
	s_cbranch_execz .LBB0_1098
	v_readlane_b32 s8, v252, 32
	v_readlane_b32 s9, v252, 33
	s_waitcnt lgkmcnt(0)
	s_nop 3
	global_load_dword v0, v145, s[8:9] sc1
	s_waitcnt vmcnt(0)
	v_cmp_eq_u32_e32 vcc, v0, v1
	s_and_saveexec_b64 s[18:19], vcc
	s_cbranch_execz .LBB0_1097
	s_mov_b32 s0, 1
	s_mov_b64 s[24:25], 0
	s_branch .LBB0_1088

.LBB0_1090:
	v_readlane_b32 s8, v252, 32
	v_readlane_b32 s9, v252, 33
	s_add_i32 s0, s0, 1
	s_mov_b64 s[40:41], -1
	s_nop 2
	global_load_dword v0, v145, s[8:9] sc1
	s_waitcnt vmcnt(0)
	v_cmp_ne_u32_e32 vcc, v0, v1
	s_orn2_b64 s[38:39], vcc, exec
	s_branch .LBB0_1087
